# A/B of the static attention priority raise: waves 0-3 raised instead of waves 4-7
# baseline (speedup 1.0000x reference)
; #define LAS __attribute__((address_space(3)))
; __device__ __forceinline__ int otid() { int t = threadIdx.x; asm volatile("" : "+v"(t)); return t; }
; __device__ __forceinline__ int v_rd_base(int lane) { return ((lane & 3) << 3) | (((lane >> 2) & 3) << 6) | (((lane >> 4) & 1) << 5) | (((lane >> 5) & 1) << 8); }
; template <int LDQ, int LDK, int LDV> ...
;     ...
;     const int tid = otid(), wid = __builtin_amdgcn_readfirstlane(tid >> 6), lane = tid & 63, r32 = lane & 31, hi = lane >> 5;
;     char* V_lds = lds; char* K_lds = lds + 3 * SHM_V;
;     LAS unsigned char* ldsl = (LAS unsigned char*)(uintptr_t)lds;
;     float* wsl = (float*)(lds + 3 * SHM_V + 3 * SHM_K) + wid * 64; float* li_l = wsl; float* al_l = wsl + 32;
;     float m_reg = -1e30f, l_reg = 0; f32x16 o[4] = {}; bf16x8 qr[ND0];
;     const bf16_t* Qw = Qb + (size_t)(wid * 32 + r32) * LDQ + hi * 8;
; #pragma unroll
;     for (int d0 = 0; d0 < ND0; ++d0) qr[d0] = *reinterpret_cast<const bf16x8*>(Qw + d0 * 16);
;     int voff[2], koff[KCH];
; #pragma unroll
;     for (int i = 0; i < 2; ++i) { const int L = (tid + 512 * i) * 16, sub = L >> 9, within = L & 511; const int kk = (sub >> 2) * 8 + (within >> 6), c = (sub & 3) * 32 + ((within & 63) >> 1);
;         const int k = (kk & ~0xC) | ((kk & 4) << 1) | ((kk & 8) >> 1); voff[i] = k * LDV + c; }
; #pragma unroll
;     for (int i = 0; i < KCH; ++i) { const int L = (tid + 512 * i) * 16, row = L / (DQK * 2), cb = (L % (DQK * 2)) ^ ((row & 7) << 4), col = cb >> 1; koff[i] = row * LDK + col; }
;     const int vb0 = (int)(uintptr_t)V_lds + v_rd_base(lane);
;     ...
;     f32x16 pA0, pA1, pB0, pB1; float mnA, mnB, alA, alB; bf16x8 pa0, pa1, pa2, pa3; const int NT = seq / 64;
;     STAGE(0, 0); STAGE(1, 64); asm volatile("s_waitcnt vmcnt(0)" ::: "memory"); __syncthreads();
.LBB0_3442:
	s_or_b64 exec, exec, s[38:39]
	s_and_saveexec_b64 s[6:7], s[0:1]
	s_xor_b64 s[0:1], exec, s[6:7]
	v_lshl_add_u32 v132, v2, 8, v224
	s_or_saveexec_b64 s[0:1], s[0:1]
	v_mov_b32_e32 v133, 0
	v_mov_b32_e32 v160, 4
	v_mov_b32_e32 v161, 0
	s_xor_b64 exec, exec, s[0:1]
	v_lshlrev_b32_e32 v4, 8, v4
	v_lshl_or_b32 v132, v3, 11, v4
	v_mov_b32_e32 v161, 0x800
	v_mov_b32_e32 v160, 36
	s_or_b64 exec, exec, s[0:1]
	v_cndmask_b32_e32 v2, v2, v3, vcc
	v_lshrrev_b32_e32 v3, 2, v154
	v_lshl_or_b32 v2, v2, 1, v3
	s_movk_i32 s0, 0x900
	v_mov_b32_e32 v8, v176
	v_mul_lo_u32 v162, v2, s0
	s_movk_i32 s7, 0x70
	v_readfirstlane_b32 s0, v8
	s_ashr_i32 s6, s0, 6
	s_and_b32 s0, s0, 0x3fffffc0
	s_lshl_b32 s0, s0, 2
	v_and_b32_e32 v155, 31, v8
	s_add_i32 s1, s0, 0
	s_lshl_b32 s0, s6, 5
	v_or_b32_e32 v2, s0, v155
	v_ashrrev_i32_e32 v3, 31, v2
	v_bfe_u32 v156, v8, 5, 1
	v_lshlrev_b64 v[2:3], 8, v[2:3]
	v_lshl_add_u64 v[0:1], v[0:1], 0, v[2:3]
	v_lshlrev_b32_e32 v178, 4, v156
	v_lshl_add_u64 v[0:1], v[0:1], 0, v[178:179]
	global_load_dwordx4 v[124:127], v[0:1], off
	global_load_dwordx4 v[120:123], v[0:1], off offset:32
	global_load_dwordx4 v[116:119], v[0:1], off offset:64
	global_load_dwordx4 v[112:115], v[0:1], off offset:96
	global_load_dwordx4 v[108:111], v[0:1], off offset:128
	global_load_dwordx4 v[104:107], v[0:1], off offset:160
	global_load_dwordx4 v[100:103], v[0:1], off offset:192
	global_load_dwordx4 v[96:99], v[0:1], off offset:224
	v_and_b32_e32 v1, 0x60, v8
	v_lshlrev_b32_e32 v2, 3, v8
	v_bfe_u32 v0, v8, 2, 2
	v_and_or_b32 v1, v2, 24, v1
	v_lshrrev_b32_e32 v2, 1, v8
	v_and_or_b32 v0, v2, 8, v0
	v_bfe_i32 v2, v8, 4, 24
	v_and_b32_e32 v3, 0x1fffff0, v2
	v_lshrrev_b32_e32 v2, 1, v2
	v_and_b32_e32 v2, 4, v2
	v_lshlrev_b32_e32 v9, 4, v8
	v_or3_b32 v2, v3, v2, v0
	v_lshl_or_b32 v134, v2, 7, v1
	v_add_u32_e32 v2, 0x2000, v9
	v_ashrrev_i32_e32 v3, 8, v2
	v_and_b32_e32 v4, 0x1fffff0, v3
	v_lshrrev_b32_e32 v3, 1, v3
	v_and_b32_e32 v3, 4, v3
	v_or3_b32 v0, v4, v3, v0
	v_lshl_or_b32 v136, v0, 7, v1
	v_bfe_i32 v0, v8, 27, 1
	v_add_u32_sdwa v0, v9, v0 dst_sel:DWORD dst_unused:UNUSED_PAD src0_sel:DWORD src1_sel:BYTE_3
	v_ashrrev_i32_e32 v0, 8, v0
	v_mul_i32_i24_e32 v1, 0x100, v0
	v_sub_u32_e32 v1, v9, v1
	v_lshlrev_b32_e32 v3, 4, v0
	v_bitop3_b32 v1, v3, v1, s7 bitop3:0x6c
	v_ashrrev_i32_e32 v1, 1, v1
	v_lshl_add_u32 v138, v0, 7, v1
	v_ashrrev_i32_e32 v0, 31, v2
	v_add_u32_sdwa v0, v2, v0 dst_sel:DWORD dst_unused:UNUSED_PAD src0_sel:DWORD src1_sel:BYTE_3
	v_ashrrev_i32_e32 v0, 8, v0
	v_mul_i32_i24_e32 v1, 0x100, v0
	v_sub_u32_e32 v1, v2, v1
	v_lshlrev_b32_e32 v2, 4, v0
	v_bitop3_b32 v1, v2, v1, s7 bitop3:0x6c
	v_add_u32_e32 v6, 0x800, v162
	v_ashrrev_i32_e32 v1, 1, v1
	s_add_i32 s1, s1, 0x18000
	v_lshl_add_u32 v140, v0, 7, v1
	v_cndmask_b32_e32 v0, v6, v162, vcc
	s_cmp_lg_u32 0, -1
	v_ashrrev_i32_e32 v1, 31, v0
	s_cselect_b32 s14, 0, 0
	v_lshlrev_b64 v[0:1], 8, v[0:1]
	s_lshl_b32 s6, s6, 10
	v_ashrrev_i32_e32 v135, 31, v134
	v_lshl_add_u64 v[2:3], s[86:87], 0, v[0:1]
	s_add_i32 s6, s14, s6
	v_lshlrev_b64 v[52:53], 1, v[134:135]
	v_ashrrev_i32_e32 v137, 31, v136
	v_lshl_add_u64 v[4:5], v[2:3], 0, v[52:53]
	s_mov_b32 m0, s6
	v_lshlrev_b64 v[54:55], 1, v[136:137]
	v_ashrrev_i32_e32 v139, 31, v138
	global_load_lds_dwordx4 v[4:5], off
	v_lshl_add_u64 v[2:3], v[2:3], 0, v[54:55]
	s_add_i32 m0, s6, 0x2000
	v_lshl_add_u64 v[0:1], s[84:85], 0, v[0:1]
	v_lshlrev_b64 v[56:57], 1, v[138:139]
	v_ashrrev_i32_e32 v141, 31, v140
	global_load_lds_dwordx4 v[2:3], off
	s_add_i32 m0, s6, 0xc000
	v_lshl_add_u64 v[2:3], v[0:1], 0, v[56:57]
	v_lshlrev_b64 v[58:59], 1, v[140:141]
	v_sub_u32_e32 v166, v6, v161
	global_load_lds_dwordx4 v[2:3], off
	v_lshl_add_u64 v[0:1], v[0:1], 0, v[58:59]
	s_add_i32 m0, s6, 0xe000
	v_cndmask_b32_e32 v60, v166, v162, vcc
	global_load_lds_dwordx4 v[0:1], off
	v_or_b32_e32 v0, 64, v60
	v_ashrrev_i32_e32 v1, 31, v0
	v_lshlrev_b64 v[0:1], 8, v[0:1]
	v_lshl_add_u64 v[2:3], s[86:87], 0, v[0:1]
	s_add_i32 m0, s6, 0x4000
	v_lshl_add_u64 v[4:5], v[2:3], 0, v[52:53]
	global_load_lds_dwordx4 v[4:5], off
	v_lshl_add_u64 v[2:3], v[2:3], 0, v[54:55]
	s_add_i32 m0, s6, 0x6000
	v_lshl_add_u64 v[0:1], s[84:85], 0, v[0:1]
	global_load_lds_dwordx4 v[2:3], off
	s_add_i32 m0, s6, 0x10000
	v_lshl_add_u64 v[2:3], v[0:1], 0, v[56:57]
	v_lshlrev_b32_e32 v10, 8, v155
	v_and_b32_e32 v11, 0x70, v9
	global_load_lds_dwordx4 v[2:3], off
	v_lshl_add_u64 v[0:1], v[0:1], 0, v[58:59]
	s_add_i32 m0, s6, 0x12000
	v_bitop3_b32 v169, v178, v10, v11 bitop3:0xde
	global_load_lds_dwordx4 v[0:1], off
	v_add_u32_e32 v4, 0, v169
	s_waitcnt vmcnt(0)
	s_waitcnt vmcnt(0) lgkmcnt(0)
	s_barrier
; template <int DQK> __device__ __forceinline__ void qkt(f32x16& p0, f32x16& p1, const char* Ks, const bf16x8* qr, int r32, int hi) {
;     p0 = f32x16{}; p1 = f32x16{};
; #pragma unroll
;     for (int d0 = 0; d0 < DQK / 16; ++d0) { const int cb = (d0 * 16 + hi * 8) * 2;
;         const bf16x8 b0 = *reinterpret_cast<const bf16x8*>(Ks + kswz<DQK>(r32, cb));
;         const bf16x8 b1 = *reinterpret_cast<const bf16x8*>(Ks + kswz<DQK>(32 + r32, cb));
;         p0 = __builtin_amdgcn_mfma_f32_32x32x16_bf16(b0, qr[d0], p0, 0, 0, 0);
;         p1 = __builtin_amdgcn_mfma_f32_32x32x16_bf16(b1, qr[d0], p1, 0, 0, 0); }
; }
; template <int LDQ, int LDK, int LDV> ...
;     ...
;     f32x16 pA0, pA1, pB0, pB1; float mnA, mnB, alA, alB; bf16x8 pa0, pa1, pa2, pa3; const int NT = seq / 64;
;     STAGE(0, 0); STAGE(1, 64); asm volatile("s_waitcnt vmcnt(0)" ::: "memory"); __syncthreads();
;     qkt<DQK>(pA0, pA1, K_lds, qr, r32, hi); partialSM(pA0, pA1, m_reg, mnA, alA, C, thr_raw);
	ds_read_b128 v[0:3], v4 offset:49152
	ds_read_b128 v[4:7], v4 offset:57344
	s_waitcnt lgkmcnt(1)
	v_mfma_f32_32x32x16_bf16 v[32:47], v[0:3], v[124:127], 0
	v_or_b32_e32 v0, 32, v178
	v_bitop3_b32 v171, v0, v10, v11 bitop3:0xde
	v_and_b32_e32 v61, 63, v8
	v_lshlrev_b32_e32 v12, 3, v61
	s_add_i32 m0, s6, 0x8000
	s_mov_b32 s44, 0
	s_mov_b32 s45, s44
	s_waitcnt lgkmcnt(0)
	v_mfma_f32_32x32x16_bf16 v[16:31], v[4:7], v[124:127], 0
	v_add_u32_e32 v4, 0, v171
	ds_read_b128 v[0:3], v4 offset:49152
	ds_read_b128 v[4:7], v4 offset:57344
	s_mov_b32 s46, s44
	s_mov_b32 s47, s44
	s_mov_b32 s48, s44
	s_mov_b32 s49, s44
	s_mov_b32 s50, s44
	s_waitcnt lgkmcnt(1)
	v_mfma_f32_32x32x16_bf16 v[32:47], v[0:3], v[120:123], v[32:47]
	v_or_b32_e32 v0, 64, v178
	v_bitop3_b32 v170, v0, v10, v11 bitop3:0xde
	s_mov_b32 s51, s44
	s_mov_b32 s52, s44
	s_mov_b32 s53, s44
	s_mov_b32 s54, s44
	s_mov_b32 s55, s44
	s_waitcnt lgkmcnt(0)
	v_mfma_f32_32x32x16_bf16 v[16:31], v[4:7], v[120:123], v[16:31]
	v_add_u32_e32 v4, 0, v170
	ds_read_b128 v[0:3], v4 offset:49152
	ds_read_b128 v[4:7], v4 offset:57344
	s_mov_b32 s56, s44
	s_mov_b32 s57, s44
	s_mov_b32 s58, s44
	s_mov_b32 s59, s44
	v_cmp_gt_u32_e64 s[38:39], 32, v61
	s_waitcnt lgkmcnt(1)
	v_mfma_f32_32x32x16_bf16 v[32:47], v[0:3], v[116:119], v[32:47]
	v_or_b32_e32 v0, 0x60, v178
	v_bitop3_b32 v168, v0, v10, v11 bitop3:0xde
	s_mov_b32 s25, 2
	s_mov_b32 s7, 1
	s_mov_b32 s22, 4
	s_movk_i32 s23, 0x100
	v_lshl_add_u32 v157, v155, 2, s1
	s_waitcnt lgkmcnt(0)
	v_mfma_f32_32x32x16_bf16 v[16:31], v[4:7], v[116:119], v[16:31]
	v_add_u32_e32 v4, 0, v168
	ds_read_b128 v[0:3], v4 offset:49152
	ds_read_b128 v[4:7], v4 offset:57344
	s_waitcnt lgkmcnt(1)
	v_mfma_f32_32x32x16_bf16 v[32:47], v[0:3], v[112:115], v[32:47]
	v_or_b32_e32 v0, 0x80, v178
	v_bitop3_b32 v167, v0, v10, v11 bitop3:0xde
	s_waitcnt lgkmcnt(0)
	v_mfma_f32_32x32x16_bf16 v[16:31], v[4:7], v[112:115], v[16:31]
	v_add_u32_e32 v4, 0, v167
	ds_read_b128 v[0:3], v4 offset:49152
	ds_read_b128 v[4:7], v4 offset:57344
	s_waitcnt lgkmcnt(1)
	v_mfma_f32_32x32x16_bf16 v[32:47], v[0:3], v[108:111], v[32:47]
	v_or_b32_e32 v0, 0xa0, v178
	v_bitop3_b32 v163, v0, v10, v11 bitop3:0xde
	s_waitcnt lgkmcnt(0)
	v_mfma_f32_32x32x16_bf16 v[16:31], v[4:7], v[108:111], v[16:31]
	v_add_u32_e32 v4, 0, v163
	ds_read_b128 v[0:3], v4 offset:49152
	ds_read_b128 v[4:7], v4 offset:57344
	s_waitcnt lgkmcnt(1)
	v_mfma_f32_32x32x16_bf16 v[32:47], v[0:3], v[104:107], v[32:47]
	v_and_b32_e32 v0, 0xc0, v9
	v_and_or_b32 v9, v12, 24, v0
	v_or_b32_e32 v0, 0xc0, v178
	v_bitop3_b32 v164, v0, v10, v11 bitop3:0xde
	v_add_u32_e32 v13, 0, v164
	ds_read_b128 v[0:3], v13 offset:49152
	s_waitcnt lgkmcnt(1)
	v_mfma_f32_32x32x16_bf16 v[16:31], v[4:7], v[104:107], v[16:31]
	v_lshlrev_b32_e32 v4, 1, v8
	v_and_b32_e32 v4, 32, v4
	v_and_b32_e32 v5, 0x100, v12
	v_or3_b32 v4, v9, v4, v5
	v_add_u32_e32 v159, s14, v4
	ds_read_b128 v[4:7], v13 offset:57344
	s_waitcnt lgkmcnt(1)
	v_mfma_f32_32x32x16_bf16 v[32:47], v[0:3], v[100:103], v[32:47]
	v_or_b32_e32 v0, 0xe0, v178
	v_bitop3_b32 v165, v0, v10, v11 bitop3:0xde
	v_add_u32_e32 v8, 0, v165
	ds_read_b128 v[0:3], v8 offset:49152
	ds_read_b128 v[48:51], v8 offset:57344
	s_waitcnt lgkmcnt(2)
	v_mfma_f32_32x32x16_bf16 v[16:31], v[4:7], v[100:103], v[16:31]
	s_waitcnt lgkmcnt(0)
; __device__ __forceinline__ void partialSM(f32x16& p0, f32x16& p1, float& m_reg, float& mn, float& alpha, const float C, const float thr_raw) {
;     float pmax = p0[0];
; #pragma unroll
;     for (int r = 1; r < 16; ++r) pmax = fmaxf(pmax, p0[r]);
; #pragma unroll
;     for (int r = 0; r < 16; ++r) pmax = fmaxf(pmax, p1[r]);
;     { auto rr = __builtin_amdgcn_permlane32_swap(__float_as_uint(pmax), __float_as_uint(pmax), false, false);
;       pmax = fmaxf(__uint_as_float(rr[0]), __uint_as_float(rr[1])); }
;     if (__builtin_expect(__all(pmax - m_reg <= thr_raw), 1)) { mn = m_reg; alpha = 1.f; }
;     else { mn = fmaxf(m_reg, pmax); alpha = __builtin_amdgcn_exp2f((m_reg - mn) * C); m_reg = mn; }
;     const float mnC = -mn * C;
; #pragma unroll
;     for (int r = 0; r < 16; ++r) p0[r] = fmaf(p0[r], C, mnC);
; #pragma unroll
;     for (int r = 0; r < 16; ++r) p1[r] = fmaf(p1[r], C, mnC);
; #pragma unroll
;     for (int r = 0; r < 16; ++r) p0[r] = __builtin_amdgcn_exp2f(p0[r]);
; template <int LDQ, int LDK, int LDV> ...
;     ...
;     qkt<DQK>(pA0, pA1, K_lds, qr, r32, hi); partialSM(pA0, pA1, m_reg, mnA, alA, C, thr_raw);
;     STAGE(2, 128);
;     int bp = 0, bc = 1, bn = 2;
	v_mfma_f32_32x32x16_bf16 v[16:31], v[48:51], v[96:99], v[16:31]
	v_or_b32_e32 v48, 0x80, v60
	v_ashrrev_i32_e32 v49, 31, v48
	v_lshlrev_b64 v[48:49], 8, v[48:49]
	v_lshl_add_u64 v[50:51], s[86:87], 0, v[48:49]
	v_lshl_add_u64 v[52:53], v[50:51], 0, v[52:53]
	global_load_lds_dwordx4 v[52:53], off
	v_lshl_add_u64 v[50:51], v[50:51], 0, v[54:55]
	s_add_i32 m0, s6, 0xa000
	v_lshl_add_u64 v[48:49], s[84:85], 0, v[48:49]
	global_load_lds_dwordx4 v[50:51], off
	s_add_i32 m0, s6, 0x14000
	v_lshl_add_u64 v[50:51], v[48:49], 0, v[56:57]
	global_load_lds_dwordx4 v[50:51], off
	v_lshl_add_u64 v[48:49], v[48:49], 0, v[58:59]
	s_add_i32 m0, s6, 0x16000
	v_mfma_f32_32x32x16_bf16 v[32:47], v[0:3], v[96:99], v[32:47]
	global_load_lds_dwordx4 v[48:49], off
	v_mov_b64_e32 v[0:1], s[44:45]
	v_mov_b64_e32 v[14:15], s[58:59]
	v_mov_b64_e32 v[2:3], s[46:47]
	v_mov_b64_e32 v[4:5], s[48:49]
	v_mov_b64_e32 v[6:7], s[50:51]
	s_nop 5
	v_max_f32_e32 v62, v33, v33
	v_max_f32_e32 v63, v32, v32
	v_max_f32_e32 v48, v63, v62
	v_max3_f32 v48, v48, v34, v35
	v_max3_f32 v48, v48, v36, v37
	v_max3_f32 v48, v48, v38, v39
	v_max3_f32 v48, v48, v40, v41
	v_max3_f32 v48, v48, v42, v43
	v_max3_f32 v48, v48, v44, v45
	v_max3_f32 v48, v48, v46, v47
	v_max3_f32 v48, v48, v16, v17
	v_max3_f32 v48, v48, v18, v19
	v_max3_f32 v48, v48, v20, v21
	v_max3_f32 v48, v48, v22, v23
	v_max3_f32 v48, v48, v24, v25
	v_max3_f32 v48, v48, v26, v27
	v_max3_f32 v48, v48, v28, v29
	v_max3_f32 v48, v48, v30, v31
	v_mov_b32_e32 v49, v48
	s_nop 1
	v_permlane32_swap_b32_e32 v48, v49
	v_max_f32_e32 v49, v49, v49
	v_max_f32_e32 v48, v48, v48
	v_max_f32_e32 v48, v48, v49
	v_add_f32_e32 v49, 0x7149f2ca, v48
	v_cmp_ge_f32_e32 vcc, s20, v49
	s_cmp_eq_u64 vcc, exec
	v_max_f32_e32 v49, 0xf149f2ca, v48
	s_cselect_b64 vcc, -1, 0
	v_mov_b32_e32 v48, 0xf149f2ca
	v_cndmask_b32_e32 v172, v49, v48, vcc
	v_mul_f32_e32 v48, 0xbe0293ee, v172
	v_fmamk_f32 v32, v32, 0x3e0293ee, v48
	v_exp_f32_e32 v206, v32
	v_fmamk_f32 v32, v33, 0x3e0293ee, v48
	v_exp_f32_e32 v209, v32
	v_fmamk_f32 v32, v34, 0x3e0293ee, v48
	v_exp_f32_e32 v207, v32
	v_fmamk_f32 v32, v35, 0x3e0293ee, v48
	v_exp_f32_e32 v210, v32
	v_fmamk_f32 v32, v36, 0x3e0293ee, v48
	v_exp_f32_e32 v208, v32
	v_fmamk_f32 v32, v37, 0x3e0293ee, v48
	v_exp_f32_e32 v211, v32
	v_fmamk_f32 v32, v38, 0x3e0293ee, v48
	v_exp_f32_e32 v204, v32
	v_fmamk_f32 v32, v39, 0x3e0293ee, v48
	v_exp_f32_e32 v205, v32
	v_fmamk_f32 v32, v40, 0x3e0293ee, v48
	v_exp_f32_e32 v200, v32
	v_fmamk_f32 v32, v41, 0x3e0293ee, v48
	v_exp_f32_e32 v202, v32
	v_fmamk_f32 v32, v42, 0x3e0293ee, v48
	v_exp_f32_e32 v201, v32
	v_fmamk_f32 v32, v43, 0x3e0293ee, v48
	v_exp_f32_e32 v203, v32
	v_fmamk_f32 v32, v44, 0x3e0293ee, v48
	v_pk_fma_f32 v[146:147], v[22:23], s[8:9], v[48:49] op_sel_hi:[1,0,0]
	v_sub_f32_e32 v22, 0xf149f2ca, v49
	v_exp_f32_e32 v196, v32
	v_fmamk_f32 v32, v45, 0x3e0293ee, v48
	v_mul_f32_e32 v22, 0x3e0293ee, v22
	v_exp_f32_e32 v198, v32
	v_fmamk_f32 v32, v46, 0x3e0293ee, v48
	v_exp_f32_e32 v22, v22
	v_exp_f32_e32 v197, v32
	v_fmamk_f32 v32, v47, 0x3e0293ee, v48
	v_exp_f32_e32 v199, v32
	v_mov_b64_e32 v[8:9], s[52:53]
	v_mov_b64_e32 v[10:11], s[54:55]
	v_mov_b64_e32 v[12:13], s[56:57]
	v_pk_fma_f32 v[142:143], v[30:31], s[8:9], v[48:49] op_sel_hi:[1,0,0]
	v_pk_fma_f32 v[128:129], v[28:29], s[8:9], v[48:49] op_sel_hi:[1,0,0]
	v_pk_fma_f32 v[130:131], v[26:27], s[8:9], v[48:49] op_sel_hi:[1,0,0]
	v_pk_fma_f32 v[144:145], v[24:25], s[8:9], v[48:49] op_sel_hi:[1,0,0]
	v_pk_fma_f32 v[148:149], v[20:21], s[8:9], v[48:49] op_sel_hi:[1,0,0]
	v_pk_fma_f32 v[150:151], v[18:19], s[8:9], v[48:49] op_sel_hi:[1,0,0]
	v_pk_fma_f32 v[152:153], v[16:17], s[8:9], v[48:49] op_sel_hi:[1,0,0]
	v_cndmask_b32_e64 v173, v22, 1.0, vcc
	v_mov_b64_e32 v[62:63], v[14:15]
	v_mov_b64_e32 v[46:47], v[14:15]
	v_mov_b64_e32 v[30:31], v[14:15]
	s_mov_b64 s[46:47], 0
	v_mov_b64_e32 v[60:61], v[12:13]
	v_mov_b64_e32 v[58:59], v[10:11]
	v_mov_b64_e32 v[56:57], v[8:9]
	v_mov_b64_e32 v[54:55], v[6:7]
	v_mov_b64_e32 v[52:53], v[4:5]
	v_mov_b64_e32 v[50:51], v[2:3]
	v_mov_b64_e32 v[48:49], v[0:1]
	v_mov_b64_e32 v[44:45], v[12:13]
	v_mov_b64_e32 v[42:43], v[10:11]
	v_mov_b64_e32 v[40:41], v[8:9]
	v_mov_b64_e32 v[38:39], v[6:7]
	v_mov_b64_e32 v[36:37], v[4:5]
	v_mov_b64_e32 v[34:35], v[2:3]
	v_mov_b64_e32 v[32:33], v[0:1]
	v_mov_b64_e32 v[28:29], v[12:13]
	v_mov_b64_e32 v[26:27], v[10:11]
	v_mov_b64_e32 v[24:25], v[8:9]
	v_mov_b64_e32 v[22:23], v[6:7]
	v_mov_b64_e32 v[20:21], v[4:5]
	v_mov_b64_e32 v[18:19], v[2:3]
	v_mov_b64_e32 v[16:17], v[0:1]
	v_readfirstlane_b32 s100, v176
	s_lshr_b32 s100, s100, 6
	s_cmp_ge_u32 s100, 4
	s_cbranch_scc1 .Lprio_skip_0
	s_setprio 1

; #define LAS __attribute__((address_space(3)))
; __device__ __forceinline__ int otid() { int t = threadIdx.x; asm volatile("" : "+v"(t)); return t; }
; __device__ __forceinline__ int v_rd_base(int lane) { return ((lane & 3) << 3) | (((lane >> 2) & 3) << 6) | (((lane >> 4) & 1) << 5) | (((lane >> 5) & 1) << 8); }
; template <int DQK, int LDQ, int LDK, int LDV> ...
;     constexpr int ND0 = DQK / 16, KCH = DQK / 64;
;     constexpr int SHM_V = 64 * 128 * 2, SHM_K = 64 * DQK * 2;
;     const int tid = otid(), wid = __builtin_amdgcn_readfirstlane(tid >> 6), lane = tid & 63, r32 = lane & 31, hi = lane >> 5;
;     char* V_lds = lds; char* K_lds = lds + 2 * SHM_V;
;     LAS unsigned char* ldsl = (LAS unsigned char*)(uintptr_t)lds;
;     float* wsl = (float*)(lds + 2 * SHM_V + 2 * SHM_K) + wid * 64; float* li_l = wsl; float* al_l = wsl + 32;
;     float m_reg = -1e30f, l_reg = 0; f32x16 o[4] = {}; bf16x8 qr[ND0];
;     const bf16_t* Qw = Qb + (size_t)(wid * 32 + r32) * LDQ + hi * 8;
; #pragma unroll
;     for (int d0 = 0; d0 < ND0; ++d0) qr[d0] = *reinterpret_cast<const bf16x8*>(Qw + (d0 < 8 ? d0 * 16 : qr_off + (d0 - 8) * 16));
;     int voff[2], koff[KCH];
; #pragma unroll
;     for (int i = 0; i < 2; ++i) { const int L = (tid + 512 * i) * 16, sub = L >> 9, within = L & 511; const int kk = (sub >> 2) * 8 + (within >> 6), c = (sub & 3) * 32 + ((within & 63) >> 1);
;         const int k = (kk & ~0xC) | ((kk & 4) << 1) | ((kk & 8) >> 1); voff[i] = k * LDV + c; }
; #pragma unroll
;     for (int i = 0; i < KCH; ++i) { const int L = (tid + 512 * i) * 16, row = L / (DQK * 2), cb = (L % (DQK * 2)) ^ ((row & 7) << 4), col = cb >> 1;
;         koff[i] = (DQK == 128 || col < 128) ? row * LDK + col : -(row * 64 + col - 128) - 1; }
;     const int vb0 = (int)(uintptr_t)V_lds + v_rd_base(lane);
.LBB0_3468:
	s_andn2_saveexec_b64 s[2:3], s[68:69]
	s_cbranch_execz .LBB0_3389
	s_movk_i32 s6, 0x7f
	v_cmp_lt_i32_e32 vcc, s6, v4
	s_movk_i32 s0, 0x80
	v_cmp_gt_i32_e64 s[0:1], s0, v4
	v_cndmask_b32_e32 v0, v4, v0, vcc
	v_cndmask_b32_e64 v1, 5, 2, vcc
	v_ashrrev_i32_e32 v2, v1, v0
	v_lshlrev_b32_e32 v1, 11, v2
	v_lshl_add_u32 v0, v2, 8, v224
	s_and_saveexec_b64 s[6:7], s[0:1]
	s_xor_b64 s[0:1], exec, s[6:7]
	v_lshlrev_b32_e32 v0, 11, v2
	v_lshlrev_b32_e32 v1, 8, v4
	s_movk_i32 s6, 0x700
	v_and_or_b32 v144, v1, s6, v0
	v_lshl_add_u32 v3, v2, 8, v224
	s_or_saveexec_b64 s[0:1], s[0:1]
	v_mov_b32_e32 v169, 0x800
	v_mov_b32_e32 v2, 34
	v_mov_b32_e32 v170, v0
	s_xor_b64 exec, exec, s[0:1]
	v_mov_b32_e32 v169, 0
	v_mov_b32_e32 v2, 2
	v_mov_b32_e32 v3, v0
	v_mov_b32_e32 v170, v1
	v_mov_b32_e32 v144, v0
	s_or_b64 exec, exec, s[0:1]
	v_lshrrev_b32_e32 v1, 3, v4
	v_cndmask_b32_e32 v1, v1, v4, vcc
	v_and_b32_e32 v1, 3, v1
	v_mov_b64_e32 v[4:5], s[80:81]
	v_mad_i64_i32 v[4:5], s[0:1], v144, s16, v[4:5]
	v_lshlrev_b32_e32 v178, 8, v1
	v_lshlrev_b32_e32 v166, 7, v1
	v_lshl_add_u64 v[6:7], v[4:5], 0, v[178:179]
	v_lshl_or_b32 v4, v1, 6, v226
	v_sub_u32_e32 v5, v4, v166
	v_mov_b32_e32 v4, v176
	v_mov_b32_e32 v147, v179
	v_readfirstlane_b32 s1, v4
	s_ashr_i32 s6, s1, 6
	v_and_b32_e32 v164, 31, v4
	s_lshl_b32 s0, s6, 5
	v_bfe_u32 v165, v4, 5, 1
	v_or_b32_e32 v8, s0, v164
	v_mad_i64_i32 v[6:7], s[22:23], v8, s16, v[6:7]
	v_lshlrev_b32_e32 v146, 4, v165
	v_lshl_add_u64 v[6:7], v[6:7], 0, v[146:147]
	global_load_dwordx4 v[140:143], v[6:7], off
	global_load_dwordx4 v[136:139], v[6:7], off offset:32
	global_load_dwordx4 v[132:135], v[6:7], off offset:64
	global_load_dwordx4 v[128:131], v[6:7], off offset:96
	global_load_dwordx4 v[124:127], v[6:7], off offset:128
	global_load_dwordx4 v[120:123], v[6:7], off offset:160
	global_load_dwordx4 v[116:119], v[6:7], off offset:192
	global_load_dwordx4 v[112:115], v[6:7], off offset:224
	v_lshlrev_b32_e32 v178, 1, v5
	v_lshl_add_u64 v[6:7], v[6:7], 0, v[178:179]
	global_load_dwordx4 v[108:111], v[6:7], off
	global_load_dwordx4 v[104:107], v[6:7], off offset:32
	global_load_dwordx4 v[100:103], v[6:7], off offset:64
	global_load_dwordx4 v[96:99], v[6:7], off offset:96
	v_lshlrev_b32_e32 v5, 4, v4
	s_mov_b32 s7, 0x2aaaaaab
	v_mul_hi_i32 v6, v5, s7
	v_lshrrev_b32_e32 v7, 31, v6
	v_ashrrev_i32_e32 v6, 6, v6
	v_add_u32_e32 v6, v6, v7
	v_mul_i32_i24_e32 v7, 0x180, v6
	v_sub_u32_e32 v7, v5, v7
	v_lshlrev_b32_e32 v8, 4, v6
	s_movk_i32 s7, 0x70
	v_bitop3_b32 v7, v8, v7, s7 bitop3:0x6c
	v_ashrrev_i32_e32 v7, 1, v7
	s_movk_i32 s7, 0x7f
	v_cmp_lt_i32_e32 vcc, s7, v7
	s_and_saveexec_b64 s[22:23], vcc
	s_xor_b64 s[38:39], exec, s[22:23]
	v_lshl_add_u32 v6, v6, 6, v7
	v_sub_u32_e32 v178, 0x7f, v6
	s_andn2_saveexec_b64 s[38:39], s[38:39]
	v_lshl_add_u32 v178, v6, 10, v7
	s_or_b64 exec, exec, s[38:39]
	v_add_u32_e32 v6, 0x2000, v5
	s_mov_b32 s7, 0x2aaaaaab
	v_mul_hi_i32 v7, v6, s7
	v_lshrrev_b32_e32 v8, 31, v7
	v_ashrrev_i32_e32 v7, 6, v7
	v_add_u32_e32 v7, v7, v8
	v_mul_i32_i24_e32 v8, 0x180, v7
	v_sub_u32_e32 v8, v6, v8
	v_lshlrev_b32_e32 v9, 4, v7
	s_movk_i32 s7, 0x70
	v_bitop3_b32 v8, v9, v8, s7 bitop3:0x6c
	v_ashrrev_i32_e32 v8, 1, v8
	s_movk_i32 s7, 0x7f
	v_cmp_lt_i32_e32 vcc, s7, v8
	s_and_saveexec_b64 s[22:23], vcc
	s_xor_b64 s[38:39], exec, s[22:23]
	v_lshl_add_u32 v7, v7, 6, v8
	v_sub_u32_e32 v148, 0x7f, v7
	s_andn2_saveexec_b64 s[38:39], s[38:39]
	v_lshl_add_u32 v148, v7, 10, v8
	s_or_b64 exec, exec, s[38:39]
	v_add_u32_e32 v8, 0x4000, v5
	s_mov_b32 s7, 0x2aaaaaab
	v_mul_hi_i32 v7, v8, s7
	v_lshrrev_b32_e32 v9, 31, v7
	v_ashrrev_i32_e32 v7, 6, v7
	v_add_u32_e32 v7, v7, v9
	v_mul_i32_i24_e32 v9, 0x180, v7
	v_sub_u32_e32 v8, v8, v9
	v_lshlrev_b32_e32 v9, 4, v7
	s_movk_i32 s7, 0x70
	v_bitop3_b32 v8, v9, v8, s7 bitop3:0x6c
	v_ashrrev_i32_e32 v8, 1, v8
	s_movk_i32 s7, 0x7f
	v_cmp_lt_i32_e32 vcc, s7, v8
	s_and_saveexec_b64 s[22:23], vcc
	s_xor_b64 s[38:39], exec, s[22:23]
	v_lshl_add_u32 v7, v7, 6, v8
	v_sub_u32_e32 v150, 0x7f, v7
	s_andn2_saveexec_b64 s[38:39], s[38:39]
	v_lshl_add_u32 v150, v7, 10, v8
	s_or_b64 exec, exec, s[38:39]
	v_lshlrev_b32_e32 v8, 9, v1
	v_mov_b32_e32 v9, v179
	v_lshl_add_u64 v[152:153], s[70:71], 0, v[8:9]
	v_and_b32_e32 v7, 0x60, v4
	v_lshrrev_b32_e32 v8, 1, v5
	v_bfe_u32 v1, v5, 6, 2
	v_and_or_b32 v7, v8, 24, v7
	v_lshrrev_b32_e32 v8, 5, v5
	v_ashrrev_i32_e32 v5, 8, v5
	v_and_or_b32 v1, v8, 8, v1
	v_and_b32_e32 v8, 0x3ffff0, v5
	v_lshrrev_b32_e32 v5, 1, v5
	v_and_b32_e32 v5, 4, v5
	v_or3_b32 v5, v8, v5, v1
	v_lshl_or_b32 v154, v5, 10, v7
	v_ashrrev_i32_e32 v5, 8, v6
	s_and_b32 s1, s1, 0x3fffffc0
; template <int DQK, int LDQ, int LDK, int LDV> ...
;     ...
;     const int NT = seq / 64;
;     STAGE(0, 0); asm volatile("s_waitcnt vmcnt(0)" ::: "memory"); __syncthreads();
	v_and_b32_e32 v6, 0x3ffff0, v5
	v_lshrrev_b32_e32 v5, 1, v5
	s_lshl_b32 s1, s1, 2
	v_and_b32_e32 v5, 4, v5
	s_add_i32 s1, s1, 0
	v_or3_b32 v1, v6, v5, v1
	s_add_i32 s1, s1, 0x14000
	v_lshl_or_b32 v156, v1, 10, v7
	v_ashrrev_i32_e32 v1, 31, v0
	s_lshl_b32 s6, s6, 10
	v_lshlrev_b64 v[6:7], 11, v[0:1]
	s_cmp_lg_u32 0, -1
	v_lshl_add_u64 v[6:7], v[152:153], 0, v[6:7]
	s_cselect_b32 s14, 0, 0
	v_ashrrev_i32_e32 v155, 31, v154
	s_add_i32 s6, s14, s6
	v_lshl_add_u64 v[8:9], v[154:155], 1, v[6:7]
	v_lshl_add_u64 v[8:9], v[8:9], 0, s[36:37]
	s_mov_b32 m0, s6
	v_ashrrev_i32_e32 v157, 31, v156
	global_load_lds_dwordx4 v[8:9], off
	v_lshl_add_u64 v[8:9], v[156:157], 1, v[6:7]
	v_lshlrev_b64 v[0:1], 7, v[0:1]
	v_lshl_add_u64 v[8:9], v[8:9], 0, s[36:37]
	s_add_i32 m0, s6, 0x2000
	v_lshl_add_u64 v[0:1], s[76:77], 0, v[0:1]
	v_not_b32_e32 v158, v178
	v_mov_b32_e32 v159, v179
	global_load_lds_dwordx4 v[8:9], off
	v_lshl_add_u64 v[8:9], v[178:179], 1, v[6:7]
	v_lshl_add_u64 v[10:11], v[158:159], 1, v[0:1]
	v_cmp_gt_i32_e64 s[40:41], 0, v178
	s_add_i32 m0, s6, 0x8000
	v_mov_b32_e32 v149, v179
	v_cndmask_b32_e64 v9, v9, v11, s[40:41]
	v_cndmask_b32_e64 v8, v8, v10, s[40:41]
	v_not_b32_e32 v160, v148
	v_mov_b32_e32 v161, v179
	global_load_lds_dwordx4 v[8:9], off
	v_lshl_add_u64 v[8:9], v[148:149], 1, v[6:7]
	v_lshl_add_u64 v[10:11], v[160:161], 1, v[0:1]
	v_cmp_gt_i32_e64 s[42:43], 0, v148
	v_mov_b32_e32 v151, v179
	v_not_b32_e32 v162, v150
	v_mov_b32_e32 v163, v179
	v_cndmask_b32_e64 v9, v9, v11, s[42:43]
	v_cndmask_b32_e64 v8, v8, v10, s[42:43]
	s_add_i32 m0, s6, 0xa000
	v_lshl_add_u64 v[6:7], v[150:151], 1, v[6:7]
	v_lshl_add_u64 v[0:1], v[162:163], 1, v[0:1]
	v_cmp_gt_i32_e64 s[44:45], 0, v150
	global_load_lds_dwordx4 v[8:9], off
	s_nop 0
	v_cndmask_b32_e64 v1, v7, v1, s[44:45]
	v_cndmask_b32_e64 v0, v6, v0, s[44:45]
	s_add_i32 m0, s6, 0xc000
	v_sub_u32_e32 v203, v3, v169
	global_load_lds_dwordx4 v[0:1], off
	v_lshlrev_b32_e32 v3, 4, v164
	v_and_b32_e32 v6, 0x70, v3
	s_movk_i32 s23, 0x60
	v_bitop3_b32 v199, v146, v6, s23 bitop3:0x36
	s_movk_i32 s23, 0x80
	v_bitop3_b32 v198, v146, v6, s23 bitop3:0x36
	s_movk_i32 s23, 0xa0
	v_bitop3_b32 v197, v146, v6, s23 bitop3:0x36
	s_movk_i32 s23, 0xc0
	v_bitop3_b32 v196, v146, v6, s23 bitop3:0x36
	s_movk_i32 s23, 0xe0
	v_and_b32_e32 v0, 63, v4
	v_bitop3_b32 v195, v146, v6, s23 bitop3:0x36
	s_movk_i32 s23, 0x100
	v_lshlrev_b32_e32 v1, 3, v0
	v_bitop3_b32 v194, v146, v6, s23 bitop3:0x36
	s_movk_i32 s23, 0x120
	v_lshlrev_b32_e32 v4, 4, v0
	v_lshlrev_b32_e32 v5, 1, v0
	v_and_b32_e32 v1, 0x118, v1
	v_bitop3_b32 v175, v146, v6, s23 bitop3:0x36
	s_movk_i32 s23, 0x140
	s_waitcnt vmcnt(0)
	v_and_b32_e32 v4, 0xc0, v4
	s_movk_i32 s22, 0x70
	v_bitop3_b32 v173, v146, v6, s23 bitop3:0x36
	s_movk_i32 s23, 0x160
	v_cmp_gt_u32_e64 s[38:39], 32, v0
	v_and_or_b32 v0, v5, 32, v1
	v_mov_b32_e32 v14, v179
	v_mov_b32_e32 v15, v179
	v_bitop3_b32 v202, v146, v3, s22 bitop3:0x78
	v_bitop3_b32 v201, v146, v6, 32 bitop3:0x36
	v_bitop3_b32 v200, v146, v6, 64 bitop3:0x36
	v_bitop3_b32 v172, v146, v6, s23 bitop3:0x36
	v_add3_u32 v167, v4, s14, v0
	v_add_u32_e32 v204, 1, v2
	v_mov_b32_e32 v0, v179
	v_mov_b32_e32 v1, v179
	v_mov_b32_e32 v2, v179
	v_mov_b32_e32 v3, v179
	v_mov_b32_e32 v4, v179
	v_mov_b32_e32 v5, v179
	v_mov_b32_e32 v6, v179
	v_mov_b32_e32 v7, v179
	v_mov_b32_e32 v8, v179
	v_mov_b32_e32 v9, v179
	v_mov_b32_e32 v10, v179
	v_mov_b32_e32 v11, v179
	v_mov_b32_e32 v12, v179
	v_mov_b32_e32 v13, v179
	v_mov_b64_e32 v[62:63], v[14:15]
	v_mov_b64_e32 v[46:47], v[14:15]
	v_mov_b64_e32 v[30:31], v[14:15]
	v_ashrrev_i32_e32 v145, 31, v144
	s_mov_b32 s7, 0
	v_mul_u32_u24_e32 v171, 0x180, v164
	s_mov_b32 s22, 64
	v_lshl_add_u32 v147, v164, 2, s1
	v_mov_b32_e32 v205, 0
	v_mov_b32_e32 v168, 0xf149f2ca
	s_mov_b64 s[48:49], 0
	v_mov_b64_e32 v[60:61], v[12:13]
	v_mov_b64_e32 v[58:59], v[10:11]
	v_mov_b64_e32 v[56:57], v[8:9]
	v_mov_b64_e32 v[54:55], v[6:7]
	v_mov_b64_e32 v[52:53], v[4:5]
	v_mov_b64_e32 v[50:51], v[2:3]
	v_mov_b64_e32 v[48:49], v[0:1]
	v_mov_b64_e32 v[44:45], v[12:13]
	v_mov_b64_e32 v[42:43], v[10:11]
	v_mov_b64_e32 v[40:41], v[8:9]
	v_mov_b64_e32 v[38:39], v[6:7]
	v_mov_b64_e32 v[36:37], v[4:5]
	v_mov_b64_e32 v[34:35], v[2:3]
	v_mov_b64_e32 v[32:33], v[0:1]
	v_mov_b64_e32 v[28:29], v[12:13]
	v_mov_b64_e32 v[26:27], v[10:11]
	v_mov_b64_e32 v[24:25], v[8:9]
	v_mov_b64_e32 v[22:23], v[6:7]
	v_mov_b64_e32 v[20:21], v[4:5]
	v_mov_b64_e32 v[18:19], v[2:3]
	v_mov_b64_e32 v[16:17], v[0:1]
	s_waitcnt vmcnt(0) lgkmcnt(0)
	s_barrier
	v_readfirstlane_b32 s100, v176
	s_lshr_b32 s100, s100, 6
	s_cmp_ge_u32 s100, 4
	s_cbranch_scc1 .Lprio_skip_1
	s_setprio 1
